# race-fixed; y correction in helper POST; recurrence writes yq and sa
# speedup vs baseline: 1.0043x; 1.0043x over previous
.LBB0_533:
	s_and_b64 vcc, exec, s[0:1]
	s_cbranch_vccz .LBB0_508
	v_mov_b32_e32 v57, v241
	s_ashr_i32 s48, s8, 5
	s_bfe_u32 s9, s8, 0x40001
	v_readfirstlane_b32 s0, v57
	s_and_b32 s10, s8, 1
	s_ashr_i32 s11, s0, 6
	s_ashr_i32 s49, s48, 31
	s_cmp_gt_i32 s11, 3
	s_mov_b64 s[0:1], -1
	s_cbranch_scc0 .LBB0_606
	s_waitcnt vmcnt(0)
	v_add_u32_e32 v198, 0xffffff00, v241
	v_lshrrev_b32_e32 v206, 3, v198
	v_and_b32_e32 v207, 7, v198
	s_lshl_b32 s0, s9, 6
	v_lshl_add_u32 v208, v207, 2, s0
	v_cmp_eq_u32_e64 s[38:39], 0, v207
	v_cmp_gt_u32_e64 s[28:29], 16, v206
	s_cmp_eq_u32 s10, 0
	s_cselect_b64 s[40:41], -1, 0
	s_nop 3
	s_and_b64 s[40:41], s[40:41], s[38:39]
	v_lshlrev_b32_e32 v199, 2, v208
	v_readlane_b32 s4, v255, 32
	v_readlane_b32 s5, v255, 33
	v_readlane_b32 s12, v255, 47
	v_readlane_b32 s13, v255, 48
	v_readlane_b32 s0, v255, 49
	v_readlane_b32 s1, v255, 50
	s_nop 4
	s_add_u32 s6, s4, 0x1000
	s_addc_u32 s7, s5, 0
	global_load_dwordx4 v[0:3], v199, s[4:5]
	global_load_dwordx4 v[4:7], v199, s[4:5] offset:128
	global_load_dwordx4 v[8:11], v199, s[6:7]
	global_load_dwordx4 v[12:15], v199, s[6:7] offset:128
	s_add_u32 s6, s4, 0x2000
	s_addc_u32 s7, s5, 0
	global_load_dwordx4 v[24:27], v199, s[12:13]
	global_load_dwordx4 v[28:31], v199, s[12:13] offset:128
	global_load_dwordx4 v[16:19], v199, s[6:7]
	global_load_dwordx4 v[20:23], v199, s[6:7] offset:128
	global_load_dwordx4 v[32:35], v199, s[0:1]
	global_load_dwordx4 v[36:39], v199, s[0:1] offset:128
	global_load_dwordx4 v[40:43], v199, s[64:65]
	global_load_dwordx4 v[44:47], v199, s[64:65] offset:128
	v_mov_b32_e32 v48, 0x3fb8aa3b
	v_mov_b32_e32 v49, 0x3fb8aa3b
	s_mul_i32 s0, s48, 0x810
	v_add_u32_e32 v209, s0, v206
	v_mov_b32_e32 v211, 0
	v_lshlrev_b32_e32 v210, 1, v208
	s_movk_i32 s14, 0x1a00
	v_mad_u64_u32 v[182:183], s[0:1], v209, s14, v[210:211]
	s_add_u32 s4, s86, 0x81a7000
	s_addc_u32 s5, s87, 0
	v_lshl_add_u64 v[182:183], v[182:183], 0, s[4:5]
	s_mov_b64 s[0:1], 0x1000
	v_lshl_add_u64 v[178:179], v[182:183], 0, s[0:1]
	v_lshl_add_u64 v[180:181], v[178:179], 0, s[0:1]
	v_lshl_add_u32 v198, v209, 11, v210
	v_mov_b32_e32 v210, v198
	s_add_u32 s4, s86, 0xeb48000
	s_addc_u32 s5, s87, 0
	v_lshl_add_u64 v[186:187], v[210:211], 0, s[4:5]
	s_add_u32 s4, s86, 0x10bc8000
	s_addc_u32 s5, s87, 0
	v_lshl_add_u64 v[188:189], v[210:211], 0, s[4:5]
	s_lshl_b32 s0, s9, 6
	s_lshl_b32 s1, s10, 5
	s_add_i32 s0, s0, s1
	v_lshl_add_u32 v198, v207, 2, s0
	v_lshlrev_b32_e32 v198, 1, v198
	v_lshl_add_u32 v210, v209, 11, v198
	s_add_u32 s4, s86, 0x5700000
	s_addc_u32 s5, s87, 0
	v_lshl_add_u64 v[190:191], v[210:211], 0, s[4:5]
	s_lshl_b32 s0, s9, 2
	v_lshl_add_u32 v210, v209, 6, s0
	s_add_u32 s4, s86, 0x7884000
	s_addc_u32 s5, s87, 0
	v_lshl_add_u64 v[192:193], v[210:211], 0, s[4:5]
	v_mul_u32_u24_e32 v194, 0x600, v206
	v_lshl_add_u32 v194, v207, 4, v194
	s_lshl_b32 s0, s10, 7
	v_mul_u32_u24_e32 v222, 0x600, v206
	v_lshl_add_u32 v222, v207, 4, v222
	v_add_u32_e32 v222, s0, v222
	v_lshlrev_b32_e32 v195, 7, v206
	v_lshl_add_u32 v195, v207, 4, v195
	v_add_u32_e32 v195, 0x18000, v195
	v_lshlrev_b32_e32 v196, 2, v206
	v_add_u32_e32 v196, 0x1a000, v196
	v_lshlrev_b32_e32 v197, 3, v206
	v_add_u32_e32 v197, 0x1a100, v197
	global_load_dwordx2 v[52:53], v[178:179], off
	global_load_dwordx2 v[54:55], v[178:179], off offset:64
	global_load_dwordx2 v[56:57], v[178:179], off offset:2048
	global_load_dwordx2 v[58:59], v[178:179], off offset:2112
	global_load_dwordx2 v[60:61], v[180:181], off
	global_load_dwordx2 v[62:63], v[180:181], off offset:64
	global_load_dwordx2 v[64:65], v[182:183], off offset:-2560
	global_load_dwordx2 v[66:67], v[182:183], off offset:-2496
	global_load_dwordx2 v[68:69], v[182:183], off offset:-512
	global_load_dwordx2 v[70:71], v[182:183], off offset:-448
	global_load_dwordx2 v[72:73], v[178:179], off offset:-2560
	global_load_dwordx2 v[74:75], v[178:179], off offset:-2496
	global_load_dwordx2 v[76:77], v[186:187], off
	global_load_dwordx2 v[78:79], v[186:187], off offset:64
	global_load_dwordx2 v[80:81], v[188:189], off
	global_load_dwordx2 v[82:83], v[188:189], off offset:64
	s_mov_b32 s13, 0
	s_waitcnt vmcnt(0)
	v_cmp_ne_u32_e64 s[6:7], 0, v206
	s_nop 3
	v_cndmask_b32_e64 v64, 0, v64, s[6:7]
	v_cndmask_b32_e64 v65, 0, v65, s[6:7]
	v_cndmask_b32_e64 v66, 0, v66, s[6:7]
	v_cndmask_b32_e64 v67, 0, v67, s[6:7]
	v_cndmask_b32_e64 v68, 0, v68, s[6:7]
	v_cndmask_b32_e64 v69, 0, v69, s[6:7]
	v_cndmask_b32_e64 v70, 0, v70, s[6:7]
	v_cndmask_b32_e64 v71, 0, v71, s[6:7]
	v_cndmask_b32_e64 v72, 0, v72, s[6:7]
	v_cndmask_b32_e64 v73, 0, v73, s[6:7]
	v_cndmask_b32_e64 v74, 0, v74, s[6:7]
	v_cndmask_b32_e64 v75, 0, v75, s[6:7]
	v_lshlrev_b32_e32 v84, 16, v52
	v_and_b32_e32 v85, 0xffff0000, v52
	v_lshlrev_b32_e32 v86, 16, v53
	v_and_b32_e32 v87, 0xffff0000, v53
	v_lshlrev_b32_e32 v88, 16, v54
	v_and_b32_e32 v89, 0xffff0000, v54
	v_lshlrev_b32_e32 v90, 16, v55
	v_and_b32_e32 v91, 0xffff0000, v55
	v_lshlrev_b32_e32 v124, 16, v64
	v_and_b32_e32 v125, 0xffff0000, v64
	v_lshlrev_b32_e32 v126, 16, v65
	v_and_b32_e32 v127, 0xffff0000, v65
	v_lshlrev_b32_e32 v128, 16, v66
	v_and_b32_e32 v129, 0xffff0000, v66
	v_lshlrev_b32_e32 v130, 16, v67
	v_and_b32_e32 v131, 0xffff0000, v67
	v_pk_add_f32 v[124:125], v[124:125], v[84:85] neg_lo:[0,1] neg_hi:[0,1]
	v_pk_add_f32 v[126:127], v[126:127], v[86:87] neg_lo:[0,1] neg_hi:[0,1]
	v_pk_add_f32 v[128:129], v[128:129], v[88:89] neg_lo:[0,1] neg_hi:[0,1]
	v_pk_add_f32 v[130:131], v[130:131], v[90:91] neg_lo:[0,1] neg_hi:[0,1]
	v_pk_fma_f32 v[84:85], v[0:1], v[124:125], v[84:85]
	v_pk_fma_f32 v[86:87], v[2:3], v[126:127], v[86:87]
	v_pk_fma_f32 v[88:89], v[4:5], v[128:129], v[88:89]
	v_pk_fma_f32 v[90:91], v[6:7], v[130:131], v[90:91]
	v_lshlrev_b32_e32 v92, 16, v56
	v_and_b32_e32 v93, 0xffff0000, v56
	v_lshlrev_b32_e32 v94, 16, v57
	v_and_b32_e32 v95, 0xffff0000, v57
	v_lshlrev_b32_e32 v96, 16, v58
	v_and_b32_e32 v97, 0xffff0000, v58
	v_lshlrev_b32_e32 v98, 16, v59
	v_and_b32_e32 v99, 0xffff0000, v59
	v_lshlrev_b32_e32 v124, 16, v68
	v_and_b32_e32 v125, 0xffff0000, v68
	v_lshlrev_b32_e32 v126, 16, v69
	v_and_b32_e32 v127, 0xffff0000, v69
	v_lshlrev_b32_e32 v128, 16, v70
	v_and_b32_e32 v129, 0xffff0000, v70
	v_lshlrev_b32_e32 v130, 16, v71
	v_and_b32_e32 v131, 0xffff0000, v71
	v_pk_add_f32 v[124:125], v[124:125], v[92:93] neg_lo:[0,1] neg_hi:[0,1]
	v_pk_add_f32 v[126:127], v[126:127], v[94:95] neg_lo:[0,1] neg_hi:[0,1]
	v_pk_add_f32 v[128:129], v[128:129], v[96:97] neg_lo:[0,1] neg_hi:[0,1]
	v_pk_add_f32 v[130:131], v[130:131], v[98:99] neg_lo:[0,1] neg_hi:[0,1]
	v_pk_fma_f32 v[92:93], v[8:9], v[124:125], v[92:93]
	v_pk_fma_f32 v[94:95], v[10:11], v[126:127], v[94:95]
	v_pk_fma_f32 v[96:97], v[12:13], v[128:129], v[96:97]
	v_pk_fma_f32 v[98:99], v[14:15], v[130:131], v[98:99]
	v_lshlrev_b32_e32 v100, 16, v60
	v_and_b32_e32 v101, 0xffff0000, v60
	v_lshlrev_b32_e32 v102, 16, v61
	v_and_b32_e32 v103, 0xffff0000, v61
	v_lshlrev_b32_e32 v104, 16, v62
	v_and_b32_e32 v105, 0xffff0000, v62
	v_lshlrev_b32_e32 v106, 16, v63
	v_and_b32_e32 v107, 0xffff0000, v63
	v_lshlrev_b32_e32 v124, 16, v72
	v_and_b32_e32 v125, 0xffff0000, v72
	v_lshlrev_b32_e32 v126, 16, v73
	v_and_b32_e32 v127, 0xffff0000, v73
	v_lshlrev_b32_e32 v128, 16, v74
	v_and_b32_e32 v129, 0xffff0000, v74
	v_lshlrev_b32_e32 v130, 16, v75
	v_and_b32_e32 v131, 0xffff0000, v75
	v_pk_add_f32 v[124:125], v[124:125], v[100:101] neg_lo:[0,1] neg_hi:[0,1]
	v_pk_add_f32 v[126:127], v[126:127], v[102:103] neg_lo:[0,1] neg_hi:[0,1]
	v_pk_add_f32 v[128:129], v[128:129], v[104:105] neg_lo:[0,1] neg_hi:[0,1]
	v_pk_add_f32 v[130:131], v[130:131], v[106:107] neg_lo:[0,1] neg_hi:[0,1]
	v_pk_fma_f32 v[100:101], v[16:17], v[124:125], v[100:101]
	v_pk_fma_f32 v[102:103], v[18:19], v[126:127], v[102:103]
	v_pk_fma_f32 v[104:105], v[20:21], v[128:129], v[104:105]
	v_pk_fma_f32 v[106:107], v[22:23], v[130:131], v[106:107]
	v_lshlrev_b32_e32 v108, 16, v80
	v_and_b32_e32 v109, 0xffff0000, v80
	v_lshlrev_b32_e32 v110, 16, v81
	v_and_b32_e32 v111, 0xffff0000, v81
	v_lshlrev_b32_e32 v112, 16, v82
	v_and_b32_e32 v113, 0xffff0000, v82
	v_lshlrev_b32_e32 v114, 16, v83
	v_and_b32_e32 v115, 0xffff0000, v83
	v_lshlrev_b32_e32 v116, 16, v76
	v_and_b32_e32 v117, 0xffff0000, v76
	v_lshlrev_b32_e32 v118, 16, v77
	v_and_b32_e32 v119, 0xffff0000, v77
	v_lshlrev_b32_e32 v120, 16, v78
	v_and_b32_e32 v121, 0xffff0000, v78
	v_lshlrev_b32_e32 v122, 16, v79
	v_and_b32_e32 v123, 0xffff0000, v79
	v_pk_mul_f32 v[132:133], v[92:93], v[24:25]
	v_pk_mul_f32 v[134:135], v[94:95], v[26:27]
	v_pk_mul_f32 v[136:137], v[96:97], v[28:29]
	v_pk_mul_f32 v[138:139], v[98:99], v[30:31]
	v_pk_add_f32 v[124:125], v[108:109], -1.0 op_sel_hi:[1,0]
	v_pk_add_f32 v[126:127], v[110:111], -1.0 op_sel_hi:[1,0]
	v_pk_add_f32 v[128:129], v[112:113], -1.0 op_sel_hi:[1,0]
	v_pk_add_f32 v[130:131], v[114:115], -1.0 op_sel_hi:[1,0]
	v_pk_fma_f32 v[124:125], v[32:33], v[124:125], 1.0 op_sel_hi:[1,1,0]
	v_pk_fma_f32 v[126:127], v[34:35], v[126:127], 1.0 op_sel_hi:[1,1,0]
	v_pk_fma_f32 v[128:129], v[36:37], v[128:129], 1.0 op_sel_hi:[1,1,0]
	v_pk_fma_f32 v[130:131], v[38:39], v[130:131], 1.0 op_sel_hi:[1,1,0]
	v_pk_mul_f32 v[140:141], v[124:125], v[92:93]
	v_pk_mul_f32 v[142:143], v[126:127], v[94:95]
	v_pk_mul_f32 v[144:145], v[128:129], v[96:97]
	v_pk_mul_f32 v[146:147], v[130:131], v[98:99]
	v_pk_mul_f32 v[148:149], v[84:85], v[140:141]
	v_pk_mul_f32 v[150:151], v[86:87], v[142:143]
	v_pk_mul_f32 v[152:153], v[88:89], v[144:145]
	v_pk_mul_f32 v[154:155], v[90:91], v[146:147]
	v_pk_mul_f32 v[156:157], v[132:133], v[108:109]
	v_pk_mul_f32 v[158:159], v[134:135], v[110:111]
	v_pk_mul_f32 v[160:161], v[136:137], v[112:113]
	v_pk_mul_f32 v[162:163], v[138:139], v[114:115]
	v_pk_mul_f32 v[124:125], v[148:149], v[40:41]
	v_pk_mul_f32 v[126:127], v[150:151], v[42:43]
	v_pk_mul_f32 v[128:129], v[152:153], v[44:45]
	v_pk_mul_f32 v[130:131], v[154:155], v[46:47]
	v_pk_add_f32 v[124:125], v[124:125], v[126:127]
	v_pk_add_f32 v[128:129], v[128:129], v[130:131]
	v_pk_add_f32 v[124:125], v[124:125], v[128:129]
	v_add_f32_e32 v173, v124, v125
	v_pk_mul_f32 v[124:125], v[156:157], v[84:85]
	v_pk_mul_f32 v[126:127], v[158:159], v[86:87]
	v_pk_mul_f32 v[128:129], v[160:161], v[88:89]
	v_pk_mul_f32 v[130:131], v[162:163], v[90:91]
	v_pk_add_f32 v[124:125], v[124:125], v[126:127]
	v_pk_add_f32 v[128:129], v[128:129], v[130:131]
	v_pk_add_f32 v[124:125], v[124:125], v[128:129]
	v_add_f32_e32 v174, v124, v125
	v_pk_mul_f32 v[124:125], v[132:133], v[132:133]
	v_pk_mul_f32 v[126:127], v[134:135], v[134:135]
	v_pk_mul_f32 v[128:129], v[136:137], v[136:137]
	v_pk_mul_f32 v[130:131], v[138:139], v[138:139]
	v_pk_add_f32 v[124:125], v[124:125], v[126:127]
	v_pk_add_f32 v[128:129], v[128:129], v[130:131]
	v_pk_add_f32 v[124:125], v[124:125], v[128:129]
	v_add_f32_e32 v172, v124, v125
	v_pk_add_f32 v[148:149], v[148:149], v[150:151]
	v_pk_add_f32 v[152:153], v[152:153], v[154:155]
	v_pk_add_f32 v[148:149], v[148:149], v[152:153]
	v_add_f32_e32 v175, v148, v149
	v_pk_mul_f32 v[116:117], v[116:117], v[48:49]
	v_pk_mul_f32 v[118:119], v[118:119], v[48:49]
	v_pk_mul_f32 v[120:121], v[120:121], v[48:49]
	v_pk_mul_f32 v[122:123], v[122:123], v[48:49]
	v_add_f32_dpp v172, v172, v172 quad_perm:[1,0,3,2] row_mask:0xf bank_mask:0xf bound_ctrl:1
	v_add_f32_dpp v173, v173, v173 quad_perm:[1,0,3,2] row_mask:0xf bank_mask:0xf bound_ctrl:1
	v_add_f32_dpp v174, v174, v174 quad_perm:[1,0,3,2] row_mask:0xf bank_mask:0xf bound_ctrl:1
	v_add_f32_dpp v175, v175, v175 quad_perm:[1,0,3,2] row_mask:0xf bank_mask:0xf bound_ctrl:1
	v_add_f32_dpp v172, v172, v172 quad_perm:[2,3,0,1] row_mask:0xf bank_mask:0xf bound_ctrl:1
	v_add_f32_dpp v173, v173, v173 quad_perm:[2,3,0,1] row_mask:0xf bank_mask:0xf bound_ctrl:1
	v_add_f32_dpp v174, v174, v174 quad_perm:[2,3,0,1] row_mask:0xf bank_mask:0xf bound_ctrl:1
	v_add_f32_dpp v175, v175, v175 quad_perm:[2,3,0,1] row_mask:0xf bank_mask:0xf bound_ctrl:1
	v_add_f32_dpp v172, v172, v172 row_half_mirror row_mask:0xf bank_mask:0xf bound_ctrl:1
	v_add_f32_dpp v173, v173, v173 row_half_mirror row_mask:0xf bank_mask:0xf bound_ctrl:1
	v_add_f32_dpp v174, v174, v174 row_half_mirror row_mask:0xf bank_mask:0xf bound_ctrl:1
	v_add_f32_dpp v175, v175, v175 row_half_mirror row_mask:0xf bank_mask:0xf bound_ctrl:1
	v_exp_f32_e32 v116, v116
	v_exp_f32_e32 v117, v117
	v_exp_f32_e32 v118, v118
	v_exp_f32_e32 v119, v119
	v_exp_f32_e32 v120, v120
	v_exp_f32_e32 v121, v121
	v_exp_f32_e32 v122, v122
	v_exp_f32_e32 v123, v123
	v_rsq_f32_e32 v176, v172
	v_pk_mul_f32 v[148:149], v[116:117], v[84:85]
	v_pk_mul_f32 v[150:151], v[118:119], v[86:87]
	v_pk_mul_f32 v[152:153], v[120:121], v[88:89]
	v_pk_mul_f32 v[154:155], v[122:123], v[90:91]
	v_min_f32_e32 v176, 0x5368d4a5, v176
	v_mul_f32_e32 v174, v174, v176
	v_pk_mul_f32 v[164:165], v[132:133], v[176:177] op_sel_hi:[1,0] neg_lo:[1,0] neg_hi:[1,0]
	v_pk_mul_f32 v[166:167], v[134:135], v[176:177] op_sel_hi:[1,0] neg_lo:[1,0] neg_hi:[1,0]
	v_pk_mul_f32 v[168:169], v[136:137], v[176:177] op_sel_hi:[1,0] neg_lo:[1,0] neg_hi:[1,0]
	v_pk_mul_f32 v[170:171], v[138:139], v[176:177] op_sel_hi:[1,0] neg_lo:[1,0] neg_hi:[1,0]
	v_pk_mul_f32 v[156:157], v[156:157], v[176:177] op_sel_hi:[1,0]
	v_pk_mul_f32 v[158:159], v[158:159], v[176:177] op_sel_hi:[1,0]
	v_pk_mul_f32 v[160:161], v[160:161], v[176:177] op_sel_hi:[1,0]
	v_pk_mul_f32 v[162:163], v[162:163], v[176:177] op_sel_hi:[1,0]
	s_mul_i32 s14, s13, 0xc000
	v_add_u32_e32 v198, s14, v194
	ds_write_b128 v198, v[148:151] offset:0
	ds_write_b128 v198, v[152:155] offset:128
	ds_write_b128 v198, v[116:119] offset:256
	ds_write_b128 v198, v[120:123] offset:384
	ds_write_b128 v198, v[140:143] offset:512
	ds_write_b128 v198, v[144:147] offset:640
	ds_write_b128 v198, v[164:167] offset:768
	ds_write_b128 v198, v[168:171] offset:896
	ds_write_b128 v198, v[156:159] offset:1024
	ds_write_b128 v198, v[160:163] offset:1152
	ds_write_b128 v198, v[100:103] offset:1280
	ds_write_b128 v198, v[104:107] offset:1408
	s_lshl_b32 s14, s13, 7
	v_add_u32_e32 v199, s14, v196
	s_lshl_b32 s14, s13, 8
	v_add_u32_e32 v198, s14, v197
	ds_write_b32 v199, v173
	ds_write_b64 v198, v[174:175]
	s_mov_b64 s[0:1], 0x34000
	v_lshl_add_u64 v[178:179], v[178:179], 0, s[0:1]
	v_lshl_add_u64 v[180:181], v[180:181], 0, s[0:1]
	v_lshl_add_u64 v[182:183], v[182:183], 0, s[0:1]
	s_mov_b64 s[0:1], 0x10000
	v_lshl_add_u64 v[186:187], v[186:187], 0, s[0:1]
	v_lshl_add_u64 v[188:189], v[188:189], 0, s[0:1]
	global_load_dwordx2 v[52:53], v[178:179], off
	global_load_dwordx2 v[54:55], v[178:179], off offset:64
	global_load_dwordx2 v[56:57], v[178:179], off offset:2048
	global_load_dwordx2 v[58:59], v[178:179], off offset:2112
	global_load_dwordx2 v[60:61], v[180:181], off
	global_load_dwordx2 v[62:63], v[180:181], off offset:64
	global_load_dwordx2 v[64:65], v[182:183], off offset:-2560
	global_load_dwordx2 v[66:67], v[182:183], off offset:-2496
	global_load_dwordx2 v[68:69], v[182:183], off offset:-512
	global_load_dwordx2 v[70:71], v[182:183], off offset:-448
	global_load_dwordx2 v[72:73], v[178:179], off offset:-2560
	global_load_dwordx2 v[74:75], v[178:179], off offset:-2496
	global_load_dwordx2 v[76:77], v[186:187], off
	global_load_dwordx2 v[78:79], v[186:187], off offset:64
	global_load_dwordx2 v[80:81], v[188:189], off
	global_load_dwordx2 v[82:83], v[188:189], off offset:64
	s_waitcnt lgkmcnt(0)
	s_barrier
	s_waitcnt vmcnt(0)
	s_mov_b32 s12, 0

.LBB0_606:
	s_and_b64 vcc, exec, s[0:1]
	s_cbranch_vccz .LBB0_508
	s_waitcnt vmcnt(0)
	v_lshrrev_b32_e32 v90, 4, v241
	v_bfe_u32 v91, v241, 3, 1
	v_and_b32_e32 v86, 15, v241
	v_lshlrev_b32_e32 v90, 1, v90
	v_lshlrev_b32_e32 v86, 4, v86
	v_add_u32_e32 v92, v90, v91
	v_xor_b32_e32 v91, 1, v91
	v_add_u32_e32 v93, v90, v91
	s_lshl_b32 s0, s10, 5
	v_lshlrev_b32_e32 v89, 2, v92
	v_add_u32_e32 v92, s0, v92
	v_add_u32_e32 v93, s0, v93
	v_add_u32_e32 v89, 0x18000, v89
	v_lshlrev_b32_e32 v87, 2, v92
	v_lshlrev_b32_e32 v88, 2, v93
	v_mov_b32_e32 v0, 0
	v_mov_b32_e32 v1, 0
	v_mov_b32_e32 v2, 0
	v_mov_b32_e32 v3, 0
	v_mov_b32_e32 v4, 0
	v_mov_b32_e32 v5, 0
	v_mov_b32_e32 v6, 0
	v_mov_b32_e32 v7, 0
	s_waitcnt lgkmcnt(0)
	s_barrier
	s_mov_b32 s4, 0
	s_nop 0
	s_nop 0
	s_nop 0
	s_nop 0
